# k26: k20 + gate-GEMM unit-head store-drain wait removed; pool epilogue gate*scale loads issued together with one wait (strategy 2 de-serialisation)
# speedup vs baseline: 1.0042x; 1.0042x over previous
; #define PG8_STAGE(bufoff, gbase, voff) do { _Pragma("unroll") for (int _i = 0; _i < 2; ++_i) \
;         __builtin_amdgcn_global_load_lds((const unsigned*)((const char*)(gbase) + (voff)[_i]), (LAS unsigned*)(lds + (bufoff) + ldsw + _i * 8192), 16, 0, 0); } while (0)
; #define PG8_LDA(dst, b, h) do { _Pragma("unroll") for (int m = 0; m < 4; ++m) _Pragma("unroll") for (int k = 0; k < 2; ++k) dst[m][k] = *(const LAS bf16x8*)(lds + PG8_SA(b, h) + aoff + m * 2048 + k * 1024); } while (0)
; #define PG8_LDB(dst, b, h) do { _Pragma("unroll") for (int n = 0; n < 2; ++n) _Pragma("unroll") for (int k = 0; k < 2; ++k) dst[n][k] = *(const LAS bf16x8*)(lds + PG8_SB(b, h) + boff + n * 2048 + k * 1024); } while (0)
; #define PG8_MMA(ai, bj, At, Bt) do { __builtin_amdgcn_s_setprio(1); _Pragma("unroll") for (int m = 0; m < 4; ++m) _Pragma("unroll") for (int n = 0; n < 2; ++n) _Pragma("unroll") for (int k = 0; k < 2; ++k) \
;         acc[ai][bj][m][n] = __builtin_amdgcn_mfma_f32_16x16x32_bf16(Bt[n][k], At[m][k], acc[ai][bj][m][n], 0, 0, 0); __builtin_amdgcn_s_setprio(0); } while (0)
; #define PG8_WAIT_L(n) asm volatile("s_waitcnt lgkmcnt(" #n ")" ::: "memory")
; #define PG8_BAR __builtin_amdgcn_s_barrier()
; #define PG8_SCHED __builtin_amdgcn_sched_barrier(0)
; template <class Epi>
; __device__ __forceinline__ void gemm_phase(LAS unsigned char* lds, const Gemm g, const Epi& E) {
;     ...
;         for (int t = 0; t < nt; t += 2) {
;             const bool last = (t == nt - 2);
;             const char* a1 = cA + (size_t)(t + 1) * kstep;
;             const char* a2 = last ? nA : cA + (size_t)(t + 2) * kstep; const char* b2 = last ? nB : cB + (size_t)(t + 2) * kstep;
;             const char* a3 = a2 + kstep; const char* b3 = b2 + kstep;
;             PG8_LDB(B0, 0, 0); PG8_SCHED; PG8_LDA(At, 0, 0); PG8_STAGE(PG8_SA(1, 1), a1 + hstepA, voffA);
;             PG8_WAIT_L(8); PG8_BAR; PG8_WAIT_L(0); PG8_MMA(0, 0, At, B0); PG8_BAR; PG8_SCHED;
;             PG8_LDB(B1, 0, 1); PG8_STAGE(PG8_SB(0, 0), b2, voffB);
;             PG8_BAR; PG8_WAIT_L(0); PG8_MMA(0, 1, At, B1); PG8_BAR;
;             PG8_LDA(At, 0, 1); PG8_STAGE(PG8_SA(0, 0), a2, voffA);
;             PG8_BAR; PG8_WAIT_L(0); PG8_MMA(1, 0, At, B0); PG8_BAR; PG8_SCHED;
.LBB0_296:
	s_add_u32 s9, s16, s5
	s_addc_u32 s18, s17, 0
	s_add_u32 s36, s9, 0x100
	s_addc_u32 s60, s18, 0
	s_and_b64 s[0:1], s[58:59], exec
	s_cselect_b32 s67, s11, s60
	s_cselect_b32 s66, s10, s36
	s_add_u32 s0, s14, s5
	s_addc_u32 s1, s15, 0
	s_add_u32 s5, s0, 0x100
	s_addc_u32 s36, s1, 0
	s_add_i32 s73, 0, 0x10000
	s_and_b64 s[0:1], s[58:59], exec
	s_cselect_b32 s75, s13, s36
	s_cselect_b32 s74, s12, s5
	s_add_u32 s78, s9, 0x40080
	s_addc_u32 s79, s18, 0
	s_add_i32 s72, s73, s30
	s_add_i32 m0, s26, 0xc000
	s_add_i32 s50, s26, 0xe000
	s_add_i32 s27, 0, 0x14000
	s_add_i32 s24, s72, 0x2000
	s_add_u32 s64, s74, 0x10000
	v_add_u32_e32 v142, s73, v159
	s_addc_u32 s65, s75, 0
	s_add_i32 s18, s27, s30
	ds_read_b128 v[130:133], v142
	ds_read_b128 v[134:137], v142 offset:1024
	ds_read_b128 v[138:141], v142 offset:2048
	ds_read_b128 v[142:145], v142 offset:3072
	s_add_i32 s36, s18, 0x2000
	s_add_i32 vcc_hi, 0, 0x18000
	s_add_u32 s60, s66, 0x40000
	s_addc_u32 s61, s67, 0
	s_add_i32 vcc_lo, vcc_hi, s30
	s_add_i32 s9, 0, 0x1c000
	s_add_i32 s5, vcc_lo, 0x2000
	s_add_u32 s58, s74, 0x10080
	s_addc_u32 s59, s75, 0
	s_add_i32 s0, s9, s30
	s_add_i32 s1, s0, 0x2000
	v_lshl_add_u64 v[192:193], s[78:79], 0, v[152:153]
	ds_read_b128 v[154:157], v160
	ds_read_b128 v[162:165], v160 offset:1024
	ds_read_b128 v[166:169], v160 offset:2048
	ds_read_b128 v[170:173], v160 offset:3072
	ds_read_b128 v[174:177], v160 offset:4096
	ds_read_b128 v[180:183], v160 offset:5120
	ds_read_b128 v[184:187], v160 offset:6144
	ds_read_b128 v[188:191], v160 offset:7168
	global_load_lds_dwordx4 v[192:193], off
	v_lshl_add_u64 v[192:193], s[78:79], 0, v[148:149]
	s_mov_b32 m0, s50
	s_nop 0
	global_load_lds_dwordx4 v[192:193], off
	s_waitcnt lgkmcnt(8)
	s_barrier
	s_waitcnt lgkmcnt(0)
	v_mfma_f32_16x16x32_bf16 v[126:129], v[130:133], v[154:157], v[126:129]
	v_mfma_f32_16x16x32_bf16 v[122:125], v[138:141], v[154:157], v[122:125]
	v_mfma_f32_16x16x32_bf16 v[114:117], v[130:133], v[166:169], v[114:117]
	v_mfma_f32_16x16x32_bf16 v[110:113], v[138:141], v[166:169], v[110:113]
	v_mfma_f32_16x16x32_bf16 v[102:105], v[130:133], v[174:177], v[102:105]
	v_mfma_f32_16x16x32_bf16 v[94:97], v[138:141], v[174:177], v[94:97]
	v_mfma_f32_16x16x32_bf16 v[86:89], v[130:133], v[184:187], v[86:89]
	v_mfma_f32_16x16x32_bf16 v[78:81], v[138:141], v[184:187], v[78:81]
	v_mfma_f32_16x16x32_bf16 v[126:129], v[134:137], v[162:165], v[126:129]
	v_mfma_f32_16x16x32_bf16 v[122:125], v[142:145], v[162:165], v[122:125]
	v_mfma_f32_16x16x32_bf16 v[114:117], v[134:137], v[170:173], v[114:117]
	v_mfma_f32_16x16x32_bf16 v[110:113], v[142:145], v[170:173], v[110:113]
	v_mfma_f32_16x16x32_bf16 v[102:105], v[134:137], v[180:183], v[102:105]
	v_mfma_f32_16x16x32_bf16 v[94:97], v[142:145], v[180:183], v[94:97]
	v_mfma_f32_16x16x32_bf16 v[86:89], v[134:137], v[188:191], v[86:89]
	v_mfma_f32_16x16x32_bf16 v[78:81], v[142:145], v[188:191], v[78:81]
	s_barrier
	s_mov_b32 m0, s72
	v_add_u32_e32 v161, s27, v159
	v_lshl_add_u64 v[208:209], s[74:75], 0, v[150:151]
	ds_read_b128 v[192:195], v161
	ds_read_b128 v[196:199], v161 offset:1024
	ds_read_b128 v[200:203], v161 offset:2048
	ds_read_b128 v[204:207], v161 offset:3072
	global_load_lds_dwordx4 v[208:209], off
	v_lshl_add_u64 v[226:227], s[74:75], 0, v[146:147]
	s_mov_b32 m0, s24
	s_nop 0
	global_load_lds_dwordx4 v[226:227], off
	s_nop 1
	s_mov_b32 m0, s26
	v_lshl_add_u64 v[228:229], s[66:67], 0, v[152:153]
	s_barrier
	s_waitcnt lgkmcnt(0)
	v_mfma_f32_16x16x32_bf16 v[118:121], v[192:195], v[154:157], v[118:121]
	v_mfma_f32_16x16x32_bf16 v[106:109], v[200:203], v[154:157], v[106:109]
	v_mfma_f32_16x16x32_bf16 v[98:101], v[192:195], v[166:169], v[98:101]
	v_mfma_f32_16x16x32_bf16 v[90:93], v[200:203], v[166:169], v[90:93]
	v_mfma_f32_16x16x32_bf16 v[82:85], v[192:195], v[174:177], v[82:85]
	v_mfma_f32_16x16x32_bf16 v[74:77], v[200:203], v[174:177], v[74:77]
	v_mfma_f32_16x16x32_bf16 v[70:73], v[192:195], v[184:187], v[70:73]
	v_mfma_f32_16x16x32_bf16 v[66:69], v[200:203], v[184:187], v[66:69]
	v_mfma_f32_16x16x32_bf16 v[118:121], v[196:199], v[162:165], v[118:121]
	v_mfma_f32_16x16x32_bf16 v[106:109], v[204:207], v[162:165], v[106:109]
	v_mfma_f32_16x16x32_bf16 v[98:101], v[196:199], v[170:173], v[98:101]
	v_mfma_f32_16x16x32_bf16 v[90:93], v[204:207], v[170:173], v[90:93]
	v_mfma_f32_16x16x32_bf16 v[82:85], v[196:199], v[180:183], v[82:85]
	v_mfma_f32_16x16x32_bf16 v[74:77], v[204:207], v[180:183], v[74:77]
	v_mfma_f32_16x16x32_bf16 v[70:73], v[196:199], v[188:191], v[70:73]
	v_mfma_f32_16x16x32_bf16 v[66:69], v[204:207], v[188:191], v[66:69]
	s_barrier
	ds_read_b128 v[154:157], v160 offset:16384
	ds_read_b128 v[162:165], v160 offset:17408
	ds_read_b128 v[166:169], v160 offset:18432
	ds_read_b128 v[170:173], v160 offset:19456
	ds_read_b128 v[174:177], v160 offset:20480
	ds_read_b128 v[180:183], v160 offset:21504
	ds_read_b128 v[184:187], v160 offset:22528
	ds_read_b128 v[188:191], v160 offset:23552
	global_load_lds_dwordx4 v[228:229], off
	v_lshl_add_u64 v[230:231], s[66:67], 0, v[148:149]
	s_mov_b32 m0, s52
	s_nop 0
	global_load_lds_dwordx4 v[230:231], off
	s_barrier
; #define PG8_STAGE(bufoff, gbase, voff) do { _Pragma("unroll") for (int _i = 0; _i < 2; ++_i) \
;         __builtin_amdgcn_global_load_lds((const unsigned*)((const char*)(gbase) + (voff)[_i]), (LAS unsigned*)(lds + (bufoff) + ldsw + _i * 8192), 16, 0, 0); } while (0)
; #define PG8_LDA(dst, b, h) do { _Pragma("unroll") for (int m = 0; m < 4; ++m) _Pragma("unroll") for (int k = 0; k < 2; ++k) dst[m][k] = *(const LAS bf16x8*)(lds + PG8_SA(b, h) + aoff + m * 2048 + k * 1024); } while (0)
; #define PG8_LDB(dst, b, h) do { _Pragma("unroll") for (int n = 0; n < 2; ++n) _Pragma("unroll") for (int k = 0; k < 2; ++k) dst[n][k] = *(const LAS bf16x8*)(lds + PG8_SB(b, h) + boff + n * 2048 + k * 1024); } while (0)
; #define PG8_MMA(ai, bj, At, Bt) do { __builtin_amdgcn_s_setprio(1); _Pragma("unroll") for (int m = 0; m < 4; ++m) _Pragma("unroll") for (int n = 0; n < 2; ++n) _Pragma("unroll") for (int k = 0; k < 2; ++k) \
;         acc[ai][bj][m][n] = __builtin_amdgcn_mfma_f32_16x16x32_bf16(Bt[n][k], At[m][k], acc[ai][bj][m][n], 0, 0, 0); __builtin_amdgcn_s_setprio(0); } while (0)
; #define PG8_WAIT_V(n) asm volatile("s_waitcnt vmcnt(" #n ")" ::: "memory")
; #define PG8_WAIT_L(n) asm volatile("s_waitcnt lgkmcnt(" #n ")" ::: "memory")
; #define PG8_BAR __builtin_amdgcn_s_barrier()
; #define PG8_SCHED __builtin_amdgcn_sched_barrier(0)
; template <class Epi>
; __device__ __forceinline__ void gemm_phase(LAS unsigned char* lds, const Gemm g, const Epi& E) {
;     ...
;             PG8_BAR; PG8_WAIT_L(0); PG8_MMA(1, 0, At, B0); PG8_BAR; PG8_SCHED;
;             PG8_STAGE(PG8_SB(0, 1), b2 + hstepB, voffB);
;             PG8_WAIT_V(6); PG8_BAR; PG8_MMA(1, 1, At, B1); PG8_BAR;
;             PG8_LDB(B0, 1, 0); PG8_SCHED; PG8_LDA(At, 1, 0); PG8_STAGE(PG8_SA(0, 1), a2 + hstepA, voffA);
;             PG8_WAIT_L(8); PG8_BAR; PG8_WAIT_L(0); PG8_MMA(0, 0, At, B0); PG8_BAR; PG8_SCHED;
;             PG8_LDB(B1, 1, 1); PG8_STAGE(PG8_SB(1, 0), b3, voffB);
;             PG8_BAR; PG8_WAIT_L(0); PG8_MMA(0, 1, At, B1); PG8_BAR;
	s_waitcnt lgkmcnt(0)
	v_mfma_f32_16x16x32_bf16 v[62:65], v[130:133], v[154:157], v[62:65]
	v_mfma_f32_16x16x32_bf16 v[58:61], v[138:141], v[154:157], v[58:61]
	v_mfma_f32_16x16x32_bf16 v[54:57], v[130:133], v[166:169], v[54:57]
	v_mfma_f32_16x16x32_bf16 v[46:49], v[138:141], v[166:169], v[46:49]
	v_mfma_f32_16x16x32_bf16 v[38:41], v[130:133], v[174:177], v[38:41]
	v_mfma_f32_16x16x32_bf16 v[30:33], v[138:141], v[174:177], v[30:33]
	v_mfma_f32_16x16x32_bf16 v[22:25], v[130:133], v[184:187], v[22:25]
	v_mfma_f32_16x16x32_bf16 v[14:17], v[138:141], v[184:187], v[14:17]
	v_mfma_f32_16x16x32_bf16 v[62:65], v[134:137], v[162:165], v[62:65]
	v_mfma_f32_16x16x32_bf16 v[58:61], v[142:145], v[162:165], v[58:61]
	v_mfma_f32_16x16x32_bf16 v[54:57], v[134:137], v[170:173], v[54:57]
	v_mfma_f32_16x16x32_bf16 v[46:49], v[142:145], v[170:173], v[46:49]
	v_mfma_f32_16x16x32_bf16 v[38:41], v[134:137], v[180:183], v[38:41]
	v_mfma_f32_16x16x32_bf16 v[30:33], v[142:145], v[180:183], v[30:33]
	v_mfma_f32_16x16x32_bf16 v[22:25], v[134:137], v[188:191], v[22:25]
	v_mfma_f32_16x16x32_bf16 v[14:17], v[142:145], v[188:191], v[14:17]
	s_barrier
	s_mov_b32 m0, s18
	v_lshl_add_u64 v[130:131], s[64:65], 0, v[150:151]
	global_load_lds_dwordx4 v[130:131], off
	v_lshl_add_u64 v[130:131], s[64:65], 0, v[146:147]
	s_mov_b32 m0, s36
	s_nop 0
	global_load_lds_dwordx4 v[130:131], off
	v_add_u32_e32 v142, vcc_hi, v159
	s_waitcnt vmcnt(6)
	s_barrier
	v_mfma_f32_16x16x32_bf16 v[50:53], v[192:195], v[154:157], v[50:53]
	v_mfma_f32_16x16x32_bf16 v[42:45], v[200:203], v[154:157], v[42:45]
	v_mfma_f32_16x16x32_bf16 v[34:37], v[192:195], v[166:169], v[34:37]
	v_mfma_f32_16x16x32_bf16 v[26:29], v[200:203], v[166:169], v[26:29]
	v_mfma_f32_16x16x32_bf16 v[18:21], v[192:195], v[174:177], v[18:21]
	v_mfma_f32_16x16x32_bf16 v[10:13], v[200:203], v[174:177], v[10:13]
	v_mfma_f32_16x16x32_bf16 v[6:9], v[192:195], v[184:187], v[6:9]
	v_mfma_f32_16x16x32_bf16 v[2:5], v[200:203], v[184:187], v[2:5]
	v_mfma_f32_16x16x32_bf16 v[50:53], v[196:199], v[162:165], v[50:53]
	v_mfma_f32_16x16x32_bf16 v[42:45], v[204:207], v[162:165], v[42:45]
	v_mfma_f32_16x16x32_bf16 v[34:37], v[196:199], v[170:173], v[34:37]
	v_mfma_f32_16x16x32_bf16 v[26:29], v[204:207], v[170:173], v[26:29]
	v_mfma_f32_16x16x32_bf16 v[18:21], v[196:199], v[180:183], v[18:21]
	v_mfma_f32_16x16x32_bf16 v[10:13], v[204:207], v[180:183], v[10:13]
	v_mfma_f32_16x16x32_bf16 v[6:9], v[196:199], v[188:191], v[6:9]
	v_mfma_f32_16x16x32_bf16 v[2:5], v[204:207], v[188:191], v[2:5]
	s_barrier
	ds_read_b128 v[130:133], v142
	ds_read_b128 v[134:137], v142 offset:1024
	ds_read_b128 v[138:141], v142 offset:2048
	ds_read_b128 v[142:145], v142 offset:3072
	s_mov_b32 m0, s53
	v_lshl_add_u64 v[192:193], s[60:61], 0, v[152:153]
	ds_read_b128 v[154:157], v160 offset:32768
	ds_read_b128 v[162:165], v160 offset:33792
	ds_read_b128 v[166:169], v160 offset:34816
	ds_read_b128 v[170:173], v160 offset:35840
	ds_read_b128 v[174:177], v160 offset:36864
	ds_read_b128 v[180:183], v160 offset:37888
	ds_read_b128 v[184:187], v160 offset:38912
	ds_read_b128 v[188:191], v160 offset:39936
	global_load_lds_dwordx4 v[192:193], off
	v_lshl_add_u64 v[192:193], s[60:61], 0, v[148:149]
	s_mov_b32 m0, s68
	s_nop 0
	global_load_lds_dwordx4 v[192:193], off
	s_waitcnt lgkmcnt(8)
	s_barrier
	s_waitcnt lgkmcnt(0)
	v_mfma_f32_16x16x32_bf16 v[126:129], v[130:133], v[154:157], v[126:129]
	v_mfma_f32_16x16x32_bf16 v[122:125], v[138:141], v[154:157], v[122:125]
	v_mfma_f32_16x16x32_bf16 v[114:117], v[130:133], v[166:169], v[114:117]
	v_mfma_f32_16x16x32_bf16 v[110:113], v[138:141], v[166:169], v[110:113]
	v_mfma_f32_16x16x32_bf16 v[102:105], v[130:133], v[174:177], v[102:105]
	v_mfma_f32_16x16x32_bf16 v[94:97], v[138:141], v[174:177], v[94:97]
	v_mfma_f32_16x16x32_bf16 v[86:89], v[130:133], v[184:187], v[86:89]
	v_mfma_f32_16x16x32_bf16 v[78:81], v[138:141], v[184:187], v[78:81]
	v_mfma_f32_16x16x32_bf16 v[126:129], v[134:137], v[162:165], v[126:129]
	v_mfma_f32_16x16x32_bf16 v[122:125], v[142:145], v[162:165], v[122:125]
	v_mfma_f32_16x16x32_bf16 v[114:117], v[134:137], v[170:173], v[114:117]
	v_mfma_f32_16x16x32_bf16 v[110:113], v[142:145], v[170:173], v[110:113]
	v_mfma_f32_16x16x32_bf16 v[102:105], v[134:137], v[180:183], v[102:105]
	v_mfma_f32_16x16x32_bf16 v[94:97], v[142:145], v[180:183], v[94:97]
	v_mfma_f32_16x16x32_bf16 v[86:89], v[134:137], v[188:191], v[86:89]
	v_mfma_f32_16x16x32_bf16 v[78:81], v[142:145], v[188:191], v[78:81]
	s_barrier
	s_mov_b32 m0, vcc_lo
	v_add_u32_e32 v161, s9, v159
	v_lshl_add_u64 v[208:209], v[208:209], 0, s[86:87]
	ds_read_b128 v[192:195], v161
	ds_read_b128 v[196:199], v161 offset:1024
	ds_read_b128 v[200:203], v161 offset:2048
	ds_read_b128 v[204:207], v161 offset:3072
	global_load_lds_dwordx4 v[208:209], off
	v_lshl_add_u64 v[208:209], v[226:227], 0, s[86:87]
	s_mov_b32 m0, s5
	s_nop 0
	global_load_lds_dwordx4 v[208:209], off
	s_nop 1
	s_mov_b32 m0, s71
	v_lshl_add_u64 v[208:209], v[228:229], 0, s[86:87]
	s_barrier
	s_waitcnt lgkmcnt(0)
	v_mfma_f32_16x16x32_bf16 v[118:121], v[192:195], v[154:157], v[118:121]
	v_mfma_f32_16x16x32_bf16 v[106:109], v[200:203], v[154:157], v[106:109]
	v_mfma_f32_16x16x32_bf16 v[98:101], v[192:195], v[166:169], v[98:101]
	v_mfma_f32_16x16x32_bf16 v[90:93], v[200:203], v[166:169], v[90:93]
	v_mfma_f32_16x16x32_bf16 v[82:85], v[192:195], v[174:177], v[82:85]
	v_mfma_f32_16x16x32_bf16 v[74:77], v[200:203], v[174:177], v[74:77]
	v_mfma_f32_16x16x32_bf16 v[70:73], v[192:195], v[184:187], v[70:73]
	v_mfma_f32_16x16x32_bf16 v[66:69], v[200:203], v[184:187], v[66:69]
	v_mfma_f32_16x16x32_bf16 v[118:121], v[196:199], v[162:165], v[118:121]
	v_mfma_f32_16x16x32_bf16 v[106:109], v[204:207], v[162:165], v[106:109]
	v_mfma_f32_16x16x32_bf16 v[98:101], v[196:199], v[170:173], v[98:101]
	v_mfma_f32_16x16x32_bf16 v[90:93], v[204:207], v[170:173], v[90:93]
	v_mfma_f32_16x16x32_bf16 v[82:85], v[196:199], v[180:183], v[82:85]
	v_mfma_f32_16x16x32_bf16 v[74:77], v[204:207], v[180:183], v[74:77]
	v_mfma_f32_16x16x32_bf16 v[70:73], v[196:199], v[188:191], v[70:73]
	v_mfma_f32_16x16x32_bf16 v[66:69], v[204:207], v[188:191], v[66:69]
	s_barrier
; #define PG8_STAGE(bufoff, gbase, voff) do { _Pragma("unroll") for (int _i = 0; _i < 2; ++_i) \
;         __builtin_amdgcn_global_load_lds((const unsigned*)((const char*)(gbase) + (voff)[_i]), (LAS unsigned*)(lds + (bufoff) + ldsw + _i * 8192), 16, 0, 0); } while (0)
; #define PG8_LDA(dst, b, h) do { _Pragma("unroll") for (int m = 0; m < 4; ++m) _Pragma("unroll") for (int k = 0; k < 2; ++k) dst[m][k] = *(const LAS bf16x8*)(lds + PG8_SA(b, h) + aoff + m * 2048 + k * 1024); } while (0)
; #define PG8_MMA(ai, bj, At, Bt) do { __builtin_amdgcn_s_setprio(1); _Pragma("unroll") for (int m = 0; m < 4; ++m) _Pragma("unroll") for (int n = 0; n < 2; ++n) _Pragma("unroll") for (int k = 0; k < 2; ++k) \
;         acc[ai][bj][m][n] = __builtin_amdgcn_mfma_f32_16x16x32_bf16(Bt[n][k], At[m][k], acc[ai][bj][m][n], 0, 0, 0); __builtin_amdgcn_s_setprio(0); } while (0)
; #define PG8_WAIT_V(n) asm volatile("s_waitcnt vmcnt(" #n ")" ::: "memory")
; #define PG8_WAIT_L(n) asm volatile("s_waitcnt lgkmcnt(" #n ")" ::: "memory")
; #define PG8_BAR __builtin_amdgcn_s_barrier()
; #define PG8_SCHED __builtin_amdgcn_sched_barrier(0)
; template <class Epi>
; __device__ __forceinline__ void gemm_phase(LAS unsigned char* lds, const Gemm g, const Epi& E) {
;     ...
;             PG8_BAR; PG8_WAIT_L(0); PG8_MMA(0, 1, At, B1); PG8_BAR;
;             PG8_LDA(At, 1, 1); PG8_STAGE(PG8_SA(1, 0), a3, voffA);
;             PG8_BAR; PG8_WAIT_L(0); PG8_MMA(1, 0, At, B0); PG8_BAR; PG8_SCHED;
;             PG8_STAGE(PG8_SB(1, 1), b3 + hstepB, voffB);
;             PG8_WAIT_V(6); PG8_BAR; PG8_MMA(1, 1, At, B1); PG8_BAR;
;     __device__ __forceinline__ void operator()(const AccT& acc, const Unit& u, int wr, int wc, int fr, int fq) const {
;     ...
;         const int gpm = mapA.src(u.pm);
;         const int mb = gpm < 32 ? 32 : (gpm - 32) >> 3;
;         const int row0 = gpm * 256 + wr * 64 + fr, col0 = u.pn * 256 + wc * 32 + 4 * fq;
;         const float* gp = modl + ((size_t)mb * 6 + gi) * 1024;
;         f32x4 gv[2][2];
; #pragma unroll
;         for (int bj = 0; bj < 2; ++bj)
; #pragma unroll
;             for (int n = 0; n < 2; ++n) { gv[bj][n] = *(const f32x4*)(gp + col0 + bj * 128 + n * 16); if (scale) gv[bj][n] = gv[bj][n] * *(const f32x4*)(scale + col0 + bj * 128 + n * 16); }
	ds_read_b128 v[154:157], v160 offset:49152
	ds_read_b128 v[162:165], v160 offset:50176
	ds_read_b128 v[166:169], v160 offset:51200
	ds_read_b128 v[170:173], v160 offset:52224
	ds_read_b128 v[174:177], v160 offset:53248
	ds_read_b128 v[180:183], v160 offset:54272
	ds_read_b128 v[184:187], v160 offset:55296
	ds_read_b128 v[188:191], v160 offset:56320
	global_load_lds_dwordx4 v[208:209], off
	v_lshl_add_u64 v[208:209], v[230:231], 0, s[86:87]
	s_mov_b32 m0, s80
	s_nop 0
	global_load_lds_dwordx4 v[208:209], off
	s_barrier
	s_waitcnt lgkmcnt(0)
	v_mfma_f32_16x16x32_bf16 v[62:65], v[130:133], v[154:157], v[62:65]
	v_mfma_f32_16x16x32_bf16 v[58:61], v[138:141], v[154:157], v[58:61]
	v_mfma_f32_16x16x32_bf16 v[54:57], v[130:133], v[166:169], v[54:57]
	v_mfma_f32_16x16x32_bf16 v[46:49], v[138:141], v[166:169], v[46:49]
	v_mfma_f32_16x16x32_bf16 v[38:41], v[130:133], v[174:177], v[38:41]
	v_mfma_f32_16x16x32_bf16 v[30:33], v[138:141], v[174:177], v[30:33]
	v_mfma_f32_16x16x32_bf16 v[22:25], v[130:133], v[184:187], v[22:25]
	v_mfma_f32_16x16x32_bf16 v[14:17], v[138:141], v[184:187], v[14:17]
	v_mfma_f32_16x16x32_bf16 v[62:65], v[134:137], v[162:165], v[62:65]
	v_mfma_f32_16x16x32_bf16 v[58:61], v[142:145], v[162:165], v[58:61]
	v_mfma_f32_16x16x32_bf16 v[54:57], v[134:137], v[170:173], v[54:57]
	v_mfma_f32_16x16x32_bf16 v[46:49], v[142:145], v[170:173], v[46:49]
	v_mfma_f32_16x16x32_bf16 v[38:41], v[134:137], v[180:183], v[38:41]
	v_mfma_f32_16x16x32_bf16 v[30:33], v[142:145], v[180:183], v[30:33]
	v_mfma_f32_16x16x32_bf16 v[22:25], v[134:137], v[188:191], v[22:25]
	v_mfma_f32_16x16x32_bf16 v[14:17], v[142:145], v[188:191], v[14:17]
	s_barrier
	s_mov_b32 m0, s0
	v_lshl_add_u64 v[130:131], s[58:59], 0, v[150:151]
	global_load_lds_dwordx4 v[130:131], off
	v_lshl_add_u64 v[130:131], s[58:59], 0, v[146:147]
	s_mov_b32 m0, s1
	s_nop 0
	global_load_lds_dwordx4 v[130:131], off
	s_waitcnt vmcnt(6)
	s_barrier
	v_mfma_f32_16x16x32_bf16 v[50:53], v[192:195], v[154:157], v[50:53]
	v_mfma_f32_16x16x32_bf16 v[42:45], v[200:203], v[154:157], v[42:45]
	v_mfma_f32_16x16x32_bf16 v[34:37], v[192:195], v[166:169], v[34:37]
	v_mfma_f32_16x16x32_bf16 v[26:29], v[200:203], v[166:169], v[26:29]
	v_mfma_f32_16x16x32_bf16 v[18:21], v[192:195], v[174:177], v[18:21]
	v_mfma_f32_16x16x32_bf16 v[10:13], v[200:203], v[174:177], v[10:13]
	v_mfma_f32_16x16x32_bf16 v[6:9], v[192:195], v[184:187], v[6:9]
	v_mfma_f32_16x16x32_bf16 v[2:5], v[200:203], v[184:187], v[2:5]
	v_mfma_f32_16x16x32_bf16 v[50:53], v[196:199], v[162:165], v[50:53]
	v_mfma_f32_16x16x32_bf16 v[42:45], v[204:207], v[162:165], v[42:45]
	v_mfma_f32_16x16x32_bf16 v[34:37], v[196:199], v[170:173], v[34:37]
	v_mfma_f32_16x16x32_bf16 v[26:29], v[204:207], v[170:173], v[26:29]
	v_mfma_f32_16x16x32_bf16 v[18:21], v[196:199], v[180:183], v[18:21]
	v_mfma_f32_16x16x32_bf16 v[10:13], v[204:207], v[180:183], v[10:13]
	v_mfma_f32_16x16x32_bf16 v[6:9], v[196:199], v[188:191], v[6:9]
	v_mfma_f32_16x16x32_bf16 v[2:5], v[204:207], v[188:191], v[2:5]
	s_movk_i32 s5, 0x100
	s_andn2_b64 vcc, exec, s[28:29]
	s_mov_b64 s[58:59], -1
	s_mov_b64 s[28:29], 0
	s_barrier
	s_cbranch_vccz .LBB0_296
	s_cmp_ge_i32 s93, s31
	s_cselect_b32 s0, s44, 0
	s_add_i32 s0, s93, s0
	s_sub_i32 s1, s0, 32
	s_lshl_b32 s4, s4, 8
	s_ashr_i32 s1, s1, 3
	s_or_b32 s4, s4, s70
	v_mov_b32_e32 v130, v1
	v_mov_b32_e32 v161, v158
	s_mul_i32 s1, s1, 6
	s_cmp_gt_i32 s0, 31
	v_readlane_b32 s14, v255, 14
	v_lshl_add_u32 v154, v130, 2, s4
	s_cselect_b32 s4, s1, 0xc0
	s_ashr_i32 s5, s4, 31
	s_lshl_b64 s[4:5], s[4:5], 12
	v_readlane_b32 s15, v255, 15
	s_add_u32 s4, s14, s4
	v_ashrrev_i32_e32 v155, 31, v154
	s_addc_u32 s5, s15, s5
	v_lshlrev_b64 v[136:137], 2, v[154:155]
	v_lshl_add_u64 v[134:135], s[4:5], 0, v[136:137]
	v_add_co_u32_e32 v130, vcc, 0x2000, v134
	v_readlane_b32 s14, v254, 30
	s_nop 0
	v_addc_co_u32_e32 v131, vcc, 0, v135, vcc
	global_load_dwordx4 v[130:133], v[130:131], off
	v_readlane_b32 s15, v254, 31
	s_andn2_b64 vcc, exec, s[14:15]
	v_lshl_add_u64 v[156:157], s[6:7], 0, v[136:137]
	v_cndmask_b32_e64 v138, 0, 1, s[14:15]
	v_cmp_ne_u32_e64 s[4:5], 1, v138
	s_mov_b64 s[14:15], 0x2000
	v_lshl_add_u64 v[142:143], v[134:135], 0, s[14:15]
	global_load_dwordx4 v[134:137], v[142:143], off offset:64
	global_load_dwordx4 v[138:141], v[142:143], off offset:512
	global_load_dwordx4 v[142:145], v[142:143], off offset:576
	s_cbranch_vccnz .LBB0_290
	global_load_dwordx4 v[162:165], v[156:157], off
	global_load_dwordx4 v[166:169], v[156:157], off offset:64
	global_load_dwordx4 v[170:173], v[156:157], off offset:512
	global_load_dwordx4 v[174:177], v[156:157], off offset:576
	s_waitcnt vmcnt(0)
	v_pk_mul_f32 v[132:133], v[132:133], v[164:165]
	v_pk_mul_f32 v[130:131], v[130:131], v[162:163]
	v_pk_mul_f32 v[136:137], v[136:137], v[168:169]
	v_pk_mul_f32 v[134:135], v[134:135], v[166:167]
	v_pk_mul_f32 v[140:141], v[140:141], v[172:173]
	v_pk_mul_f32 v[138:139], v[138:139], v[170:171]
	v_pk_mul_f32 v[144:145], v[144:145], v[176:177]
	v_pk_mul_f32 v[142:143], v[142:143], v[174:175]
	s_branch .LBB0_290

; template <class Epi>
; __device__ __forceinline__ void gemm_phase(LAS unsigned char* lds, const Gemm g, const Epi& E) {
;     ...
;         const char* nA = has_next ? (const char*)g.A + (size_t)g.mapA.src(nxt.pm) * tstepA + (size_t)nxt.pn * g.a_pn_step : cA;
;         const char* nB = has_next ? (const char*)g.Bt + (size_t)g.mapB.src(nxt.pn) * tstepB : cB;
;         for (int t = 0; t < nt; t += 2) {
;             const bool last = (t == nt - 2);
;             const char* a1 = cA + (size_t)(t + 1) * kstep;
;             const char* a2 = last ? nA : cA + (size_t)(t + 2) * kstep; const char* b2 = last ? nB : cB + (size_t)(t + 2) * kstep;
;             const char* a3 = a2 + kstep; const char* b3 = b2 + kstep;
;     ...
; #pragma unroll
;         for (int a = 0; a < 2; ++a)
; #pragma unroll
;             for (int b = 0; b < 2; ++b)
; #pragma unroll
;                 for (int m = 0; m < 4; ++m)
; #pragma unroll
;                     for (int n = 0; n < 2; ++n) acc[a][b][m][n] = (f32x4){0.f, 0.f, 0.f, 0.f};
;         cur = nxt; cA = nA; cB = nB; ++ui;
.LBB0_474:
	s_ashr_i32 s9, s8, 31
	s_lshl_b64 s[28:29], s[8:9], 19
	v_readlane_b32 s9, v255, 28
	s_add_u32 s9, s9, s28
	v_readlane_b32 s28, v255, 29
	s_addc_u32 s28, s28, s29
	s_and_b64 s[4:5], s[4:5], exec
	s_cselect_b32 s5, s28, s17
	s_cselect_b32 s4, s9, s16
	s_add_u32 s14, s14, 0x40080
	s_addc_u32 s15, s15, 0
	s_add_u32 s9, s16, 0x100
	v_mov_b32_e32 v2, 0
	s_addc_u32 s53, s17, 0
	s_mov_b32 s65, -2
	v_mov_b32_e32 v3, v2
	v_mov_b32_e32 v4, v2
	v_mov_b32_e32 v5, v2
	v_mov_b32_e32 v6, v2
	v_mov_b32_e32 v7, v2
	v_mov_b32_e32 v8, v2
	v_mov_b32_e32 v9, v2
	v_mov_b32_e32 v18, v2
	v_mov_b32_e32 v19, v2
	v_mov_b32_e32 v20, v2
	v_mov_b32_e32 v21, v2
	v_mov_b32_e32 v22, v2
	v_mov_b32_e32 v23, v2
	v_mov_b32_e32 v24, v2
	v_mov_b32_e32 v25, v2
	v_mov_b32_e32 v34, v2
	v_mov_b32_e32 v35, v2
	v_mov_b32_e32 v36, v2
	v_mov_b32_e32 v37, v2
	v_mov_b32_e32 v38, v2
	v_mov_b32_e32 v39, v2
	v_mov_b32_e32 v40, v2
	v_mov_b32_e32 v41, v2
	v_mov_b32_e32 v50, v2
	v_mov_b32_e32 v51, v2
	v_mov_b32_e32 v52, v2
	v_mov_b32_e32 v53, v2
	v_mov_b32_e32 v54, v2
	v_mov_b32_e32 v55, v2
	v_mov_b32_e32 v56, v2
	v_mov_b32_e32 v57, v2
	v_mov_b32_e32 v10, v2
	v_mov_b32_e32 v11, v2
	v_mov_b32_e32 v12, v2
	v_mov_b32_e32 v13, v2
	v_mov_b32_e32 v14, v2
	v_mov_b32_e32 v15, v2
	v_mov_b32_e32 v16, v2
	v_mov_b32_e32 v17, v2
	v_mov_b32_e32 v26, v2
	v_mov_b32_e32 v27, v2
	v_mov_b32_e32 v28, v2
	v_mov_b32_e32 v29, v2
	v_mov_b32_e32 v30, v2
	v_mov_b32_e32 v31, v2
	v_mov_b32_e32 v32, v2
	v_mov_b32_e32 v33, v2
	v_mov_b32_e32 v42, v2
	v_mov_b32_e32 v43, v2
	v_mov_b32_e32 v44, v2
	v_mov_b32_e32 v45, v2
	v_mov_b32_e32 v46, v2
	v_mov_b32_e32 v47, v2
	v_mov_b32_e32 v48, v2
	v_mov_b32_e32 v49, v2
	v_mov_b32_e32 v58, v2
	v_mov_b32_e32 v59, v2
	v_mov_b32_e32 v60, v2
	v_mov_b32_e32 v61, v2
	v_mov_b32_e32 v62, v2
	v_mov_b32_e32 v63, v2
	v_mov_b32_e32 v64, v2
	v_mov_b32_e32 v65, v2
	v_mov_b32_e32 v74, v2
	v_mov_b32_e32 v75, v2
	v_mov_b32_e32 v76, v2
	v_mov_b32_e32 v77, v2
	v_mov_b32_e32 v78, v2
	v_mov_b32_e32 v79, v2
	v_mov_b32_e32 v80, v2
	v_mov_b32_e32 v81, v2
	v_mov_b32_e32 v98, v2
	v_mov_b32_e32 v99, v2
	v_mov_b32_e32 v100, v2
	v_mov_b32_e32 v101, v2
	v_mov_b32_e32 v102, v2
	v_mov_b32_e32 v103, v2
	v_mov_b32_e32 v104, v2
	v_mov_b32_e32 v105, v2
	v_mov_b32_e32 v114, v2
	v_mov_b32_e32 v115, v2
	v_mov_b32_e32 v116, v2
	v_mov_b32_e32 v117, v2
	v_mov_b32_e32 v118, v2
	v_mov_b32_e32 v119, v2
	v_mov_b32_e32 v120, v2
	v_mov_b32_e32 v121, v2
	v_mov_b32_e32 v130, v2
	v_mov_b32_e32 v131, v2
	v_mov_b32_e32 v132, v2
	v_mov_b32_e32 v133, v2
	v_mov_b32_e32 v134, v2
	v_mov_b32_e32 v135, v2
	v_mov_b32_e32 v136, v2
	v_mov_b32_e32 v137, v2
	v_mov_b32_e32 v90, v2
	v_mov_b32_e32 v91, v2
	v_mov_b32_e32 v92, v2
	v_mov_b32_e32 v93, v2
	v_mov_b32_e32 v94, v2
	v_mov_b32_e32 v95, v2
	v_mov_b32_e32 v96, v2
	v_mov_b32_e32 v97, v2
	v_mov_b32_e32 v106, v2
	v_mov_b32_e32 v107, v2
	v_mov_b32_e32 v108, v2
	v_mov_b32_e32 v109, v2
	v_mov_b32_e32 v110, v2
	v_mov_b32_e32 v111, v2
	v_mov_b32_e32 v112, v2
	v_mov_b32_e32 v113, v2
	v_mov_b32_e32 v122, v2
	v_mov_b32_e32 v123, v2
	v_mov_b32_e32 v124, v2
	v_mov_b32_e32 v125, v2
	v_mov_b32_e32 v126, v2
	v_mov_b32_e32 v127, v2
	v_mov_b32_e32 v128, v2
	v_mov_b32_e32 v129, v2
	v_mov_b32_e32 v138, v2
	v_mov_b32_e32 v139, v2
	v_mov_b32_e32 v140, v2
	v_mov_b32_e32 v141, v2
	v_mov_b32_e32 v142, v2
	v_mov_b32_e32 v143, v2
	v_mov_b32_e32 v144, v2
	v_mov_b32_e32 v145, v2
